# attention tile loop: v_max3 tree for the row max, K/V staging and next-tile address invariants hoisted out of the tile loop
# speedup vs baseline: 1.0009x; 1.0009x over previous
; #define LAS __attribute__((address_space(3)))
; #define FRESH_KP KP Pp; { unsigned long long ki_ = (unsigned long long)__builtin_amdgcn_kernarg_segment_ptr(); asm volatile("" : "+s"(ki_)); Pp = (KP)ki_; }
; __device__ __forceinline__ void attn_mfma(LAS unsigned char* lds, int layer, int G, const int wave_s) {
;     FRESH_IDS; FRESH_KP;
;     unsigned char* ws = Pp->ws;
;     const bf16_t* Q = (const bf16_t*)(ws + WS_Q); const bf16_t* Kb = (const bf16_t*)(ws + WS_K); const bf16_t* Vb = (const bf16_t*)(ws + WS_V);
;     bf16_t* YM = (bf16_t*)(ws + WS_YM); const float* ZT = (const float*)(ws + WS_SSHY);
;     const float* gat = Pp->in[20] + layer * ATTW; const float* ghy = Pp->in[19] + layer * HY;
;     const int r32 = lane & 31, hi = lane >> 5, h = wave, kv = h >> 2;
;     const float sk = Pp->in[18][layer * NH + h] * LOG2E;
;     const unsigned lbase = (unsigned)(uintptr_t)lds;
;     LAS float* al_l = (LAS float*)(lds + AT_SCR) + wave * 64; LAS float* li_l = al_l + 32;
;     LAS float* xa = (LAS float*)(lds + AT_XA); LAS float* xh = (LAS float*)(lds + AT_XH);
;     const int nunits = layer == DEPTH - 1 ? ML / 32 : MT / 32;
;     for (int unit = blockIdx.x; unit < nunits; unit += G) {
.LBB0_785:
	s_andn2_b64 vcc, exec, s[36:37]
	s_cbranch_vccnz .LBB0_884
	s_cmp_lg_u32 s76, 3
	s_cselect_b64 s[44:45], -1, 0
	s_and_b64 s[0:1], s[44:45], exec
	s_movk_i32 s0, 0x110
	s_cselect_b32 s0, s0, 0x100
	s_cmp_ge_i32 s2, s0
	v_readlane_b32 s17, v253, 2
	s_mov_b64 s[36:37], s[94:95]
	v_mbcnt_lo_u32_b32 v0, -1, 0
	v_mbcnt_hi_u32_b32 v0, -1, v0
	s_cbranch_scc1 .LBB0_826
	s_load_dwordx2 s[40:41], s[36:37], 0xd8
	s_lshl_b32 s10, s76, 3
	s_lshl_b32 s1, s17, 6
	v_and_b32_e32 v184, 31, v0
	s_waitcnt vmcnt(0)
	v_lshlrev_b32_e32 v4, 4, v0
	s_waitcnt lgkmcnt(0)
	s_add_u32 s46, s40, 0xac20000
	s_addc_u32 s47, s41, 0
	s_add_u32 s48, s40, 0xb060000
	s_addc_u32 s49, s41, 0
	s_add_u32 s42, s40, 0xb4a0000
	s_addc_u32 s43, s41, 0
	s_add_i32 s10, s17, s10
	s_ashr_i32 s11, s10, 31
	s_lshl_b64 s[38:39], s[10:11], 2
	s_load_dwordx2 s[10:11], s[36:37], 0x90
	s_load_dwordx4 s[52:55], s[36:37], 0x98
	v_and_b32_e32 v6, 0xc0, v4
	v_lshlrev_b32_e32 v7, 1, v0
	v_and_b32_e32 v7, 32, v7
	s_waitcnt lgkmcnt(0)
	s_add_u32 s10, s10, s38
	s_addc_u32 s11, s11, s39
	global_load_dword v2, v1, s[10:11]
	s_lshl_b32 s10, s17, 8
	s_add_i32 s15, s10, 0
	s_lshl_b32 s26, s76, 10
	s_add_i32 s15, s15, 0x20000
	s_lshl_b64 s[10:11], s[26:27], 2
	s_add_u32 s56, s52, s10
	s_addc_u32 s57, s53, s11
	s_add_u32 s54, s54, s10
	s_addc_u32 s55, s55, s11
	s_lshl_b32 s60, s17, 7
	s_ashr_i32 s61, s60, 31
	s_lshl_b64 s[52:53], s[60:61], 1
	s_add_u32 s10, s40, s52
	s_addc_u32 s11, s41, s53
	s_add_u32 s50, s10, 0x9b20000
	s_addc_u32 s51, s11, 0
	s_lshl_b32 s10, s17, 12
	s_and_b32 s10, s10, 0xffffc000
	s_add_i32 s11, s10, 0
	v_lshl_add_u32 v188, v184, 8, s11
	s_add_i32 s11, 0, 0x8000
	v_add_u32_e32 v6, s11, v6
	v_ashrrev_i32_e32 v185, 5, v0
	v_mov_b32_e32 v163, v1
	s_mulk_i32 s17, 0x2200
	v_lshlrev_b32_e32 v187, 4, v185
	v_cmp_gt_u32_e64 s[36:37], 32, v0
	s_mov_b64 s[28:29], 0xd6a0000
	s_add_i32 s17, s17, 0
	v_ashrrev_i32_e32 v194, 4, v0
	v_lshl_add_u32 v193, v184, 1, s17
	v_lshlrev_b32_e32 v189, 2, v185
	v_lshlrev_b32_e32 v5, 2, v184
	v_readlane_b32 s23, v255, 7
	s_add_i32 s11, s60, 0
	s_add_i32 s11, s11, 0x20c00
	v_add_u32_e32 v190, s15, v5
	v_add_u32_e32 v209, s15, v187
	s_movk_i32 s15, 0x440
	v_cmp_eq_u32_e64 s[38:39], 0, v184
	s_waitcnt vmcnt(0)
	v_mul_f32_e32 v186, 0x3fb8aa3b, v2
	v_lshlrev_b32_e32 v2, 3, v0
	v_and_b32_e32 v3, 24, v2
	v_and_b32_e32 v2, 0x100, v2
	v_add3_u32 v3, v6, v3, v7
	v_add3_u32 v191, v3, v2, s10
	v_and_b32_e32 v2, 7, v0
	v_lshlrev_b32_e32 v162, 4, v2
	v_and_b32_e32 v6, -8, v0
	v_lshlrev_b32_e32 v192, 2, v2
	v_lshl_add_u64 v[2:3], s[40:41], 0, v[162:163]
	v_cmp_gt_i32_e64 s[40:41], 8, v0
	v_and_b32_e32 v0, 0xf0, v4
	v_lshl_add_u64 v[164:165], v[2:3], 0, s[28:29]
	v_add_u32_e32 v196, s17, v0
	s_movk_i32 s17, 0x70
	v_add_u32_e32 v3, 32, v187
	v_bitop3_b32 v202, v3, v4, s17 bitop3:0x78
	v_add_u32_e32 v3, 64, v187
	v_bitop3_b32 v203, v3, v4, s17 bitop3:0x78
	v_add_u32_e32 v3, 0x60, v187
	v_bitop3_b32 v204, v3, v4, s17 bitop3:0x78
	v_add_u32_e32 v3, 0x80, v187
	v_bitop3_b32 v205, v3, v4, s17 bitop3:0x78
	v_add_u32_e32 v3, 0xa0, v187
	v_bitop3_b32 v206, v3, v4, s17 bitop3:0x78
	v_add_u32_e32 v3, 0xc0, v187
	v_bitop3_b32 v207, v3, v4, s17 bitop3:0x78
	v_add_u32_e32 v3, 0xe0, v187
	v_or_b32_e32 v2, s60, v184
	v_bitop3_b32 v200, v187, v4, s17 bitop3:0x78
	v_bitop3_b32 v208, v3, v4, s17 bitop3:0x78
	v_add_u32_e32 v4, s1, v6
	s_mov_b32 s17, 0x8800
	v_add_u32_e32 v6, 0x200, v4
	v_ashrrev_i32_e32 v3, 31, v2
	s_add_i32 s10, s23, s60
	v_add_u32_e32 v163, s23, v5
	s_movk_i32 s23, 0x110
	v_mad_i64_i32 v[166:167], s[28:29], v4, s17, 0
	v_mad_i64_i32 v[168:169], s[28:29], v6, s17, 0
	v_lshl_add_u64 v[180:181], v[2:3], 2, s[54:55]
	v_or_b32_e32 v3, 1, v189
	v_mul_lo_u32 v198, v194, s23
	v_ashrrev_i32_e32 v5, 31, v4
	v_mul_lo_u32 v210, v3, s23
	s_add_u32 s28, s42, s52
	v_ashrrev_i32_e32 v7, 31, v6
	v_lshl_add_u64 v[174:175], v[4:5], 2, s[56:57]
	v_lshl_add_u64 v[176:177], v[4:5], 1, s[42:43]
	v_mul_lo_u32 v2, v185, s15
	v_add_u32_e32 v3, 0x990, v210
	v_add_u32_e32 v4, 0x440, v198
	s_addc_u32 s29, s43, s53
	v_lshl_add_u64 v[178:179], v[6:7], 1, s[42:43]
	v_lshl_add_u64 v[182:183], s[28:29], 0, v[0:1]
	v_add_u32_e32 v211, v193, v2
	v_add_u32_e32 v212, v193, v3
	v_add_u32_e32 v213, v196, v4
	v_mbcnt_lo_u32_b32 v66, -1, 0
	v_mbcnt_hi_u32_b32 v66, -1, v66
	v_add_u32_e32 v67, s1, v66
	v_ashrrev_i32_e32 v68, 4, v67
	v_and_b32_e32 v70, 0xfffff0, v68
	v_lshlrev_b32_e32 v71, 1, v68
	v_lshlrev_b32_e32 v66, 3, v66
	v_and_or_b32 v70, v71, 8, v70
	v_and_b32_e32 v69, 0x78, v66
	v_lshrrev_b32_e32 v70, 1, v70
	v_bfe_u32 v66, v66, 5, 2
	v_lshrrev_b32_e32 v71, 1, v68
	v_or_b32_e32 v66, v70, v66
	v_and_b32_e32 v70, 3, v68
	v_lshlrev_b32_e32 v69, 1, v69
	v_and_or_b32 v70, v71, 4, v70
	v_and_b32_e32 v71, 48, v69
	v_lshlrev_b32_e32 v68, 8, v68
	v_and_b32_e32 v67, 0x70, v67
	v_lshl_or_b32 v70, v70, 6, v71
	v_bitop3_b32 v67, v69, v68, v67 bitop3:0xde
	v_lshl_or_b32 v66, v66, 9, v70
	v_mov_b32_e32 v233, v67
	v_mov_b32_e32 v234, v66
	v_mbcnt_lo_u32_b32 v236, -1, 0
	v_mbcnt_hi_u32_b32 v236, -1, v236
	v_add_u32_e32 v235, s1, v236
	v_ashrrev_i32_e32 v235, 4, v235
	v_lshlrev_b32_e32 v236, 4, v236
	v_and_b32_e32 v236, 0xf0, v236
	s_mov_b32 s15, s2
	s_branch .LBB0_789

.LBB0_796:
	s_cmp_ge_u32 s53, s26
	s_cbranch_scc1 .Lkv_skip
	s_add_i32 s7, s69, s23
	s_add_i32 s7, s7, 1
	s_lshl_b32 s7, s7, 6
	s_add_i32 s7, s7, s28
	s_add_i32 s14, s60, s68
	s_cmp_lt_u32 s53, s25
	s_cselect_b64 s[12:13], -1, 0
	s_cselect_b32 s14, s7, s14
	s_cselect_b32 s16, s29, s35
	v_add_u32_e32 v225, s14, v235
	v_med3_i32 v228, v225, 0, v237
	v_cndmask_b32_e64 v228, v225, v228, s[12:13]
	v_add_u32_e32 v228, s16, v228
	v_ashrrev_i32_e32 v229, 31, v228
	v_lshlrev_b64 v[228:229], 9, v[228:229]
	v_or_b32_e32 v228, v228, v236
	v_lshl_add_u64 v[230:231], s[46:47], 0, v[228:229]
	v_lshl_add_u64 v[228:229], s[48:49], 0, v[228:229]
	global_load_dwordx4 v[130:133], v[230:231], off
	global_load_dwordx4 v[134:137], v[230:231], off offset:256
	global_load_dwordx4 v[138:141], v[228:229], off
	global_load_dwordx4 v[142:145], v[228:229], off offset:256
	v_add_u32_e32 v228, 32, v225
	v_med3_i32 v229, v228, 0, v237
	v_cndmask_b32_e64 v228, v228, v229, s[12:13]
	v_add_u32_e32 v228, s16, v228
	v_ashrrev_i32_e32 v229, 31, v228
	v_lshlrev_b64 v[228:229], 9, v[228:229]
	v_or_b32_e32 v228, v228, v236
	v_lshl_add_u64 v[230:231], s[46:47], 0, v[228:229]
	v_lshl_add_u64 v[228:229], s[48:49], 0, v[228:229]
	global_load_dwordx4 v[146:149], v[230:231], off
	global_load_dwordx4 v[150:153], v[230:231], off offset:256
	global_load_dwordx4 v[154:157], v[228:229], off
	global_load_dwordx4 v[158:161], v[228:229], off offset:256

; __device__ __forceinline__ int crow(int r, int hi) { return (r & 3) + 8 * (r >> 2) + 4 * hi; }
; __device__ __forceinline__ void attn_mfma(LAS unsigned char* lds, int layer, int G, const int wave_s) {
;     ...
;             float pmax = fmaxf(p0[0], p1[0]);
; #pragma unroll
;             for (int r = 1; r < 16; ++r) pmax = fmaxf(pmax, fmaxf(p0[r], p1[r]));
;             { auto rr = __builtin_amdgcn_permlane32_swap(__float_as_uint(pmax), __float_as_uint(pmax), false, false); pmax = fmaxf(__uint_as_float(rr[0]), __uint_as_float(rr[1])); }
;             const float mn = fmaxf(m_reg, pmax), alpha = __builtin_amdgcn_exp2f(m_reg - mn); m_reg = mn;
;             float ps = 0.f;
; #pragma unroll
;             for (int r = 0; r < 16; ++r) { p0[r] = __builtin_amdgcn_exp2f(p0[r] - mn); p1[r] = __builtin_amdgcn_exp2f(p1[r] - mn); ps += p0[r] + p1[r]; }
;             { auto rr = __builtin_amdgcn_permlane32_swap(__float_as_uint(ps), __float_as_uint(ps), false, false); ps = __uint_as_float(rr[0]) + __uint_as_float(rr[1]); }
;             l_reg = l_reg * alpha + ps;
;             if (__any(alpha < 1.f)) { if (hi == 0) al_l[r32] = alpha; asm volatile("s_waitcnt lgkmcnt(0)" ::: "memory");
; #pragma unroll
;                 for (int d = 0; d < 4; ++d)
; #pragma unroll
;                     for (int r = 0; r < 16; ++r) o[d][r] *= al_l[crow(r, hi)]; }
.LBB0_798:
	s_nop 10
	v_max3_f32 v0, v66, v67, v68
	v_max3_f32 v199, v69, v70, v71
	v_max3_f32 v218, v72, v73, v74
	v_max3_f32 v219, v75, v76, v77
	v_max3_f32 v0, v0, v78, v79
	v_max3_f32 v199, v199, v80, v81
	v_max3_f32 v218, v218, v82, v83
	v_max3_f32 v219, v219, v84, v85
	v_max3_f32 v0, v0, v86, v87
	v_max3_f32 v199, v199, v88, v89
	v_max3_f32 v218, v218, v90, v91
	v_max3_f32 v219, v219, v92, v93
	v_max3_f32 v0, v0, v94, v95
	v_max3_f32 v199, v199, v96, v97
	v_max3_f32 v0, v0, v199, v218
	v_max_f32_e32 v0, v0, v219
	v_mov_b32_e32 v199, v0
	s_nop 1
	v_permlane32_swap_b32_e32 v0, v199
	v_max3_f32 v0, v217, v0, v199
	v_sub_f32_e32 v66, v66, v0
	v_sub_f32_e32 v82, v82, v0
	v_exp_f32_e32 v66, v66
	v_exp_f32_e32 v218, v82
	v_sub_f32_e32 v67, v67, v0
	v_sub_f32_e32 v82, v83, v0
	v_exp_f32_e32 v67, v67
	v_exp_f32_e32 v219, v82
	v_sub_f32_e32 v68, v68, v0
	v_sub_f32_e32 v84, v84, v0
	v_sub_f32_e32 v82, v217, v0
	v_exp_f32_e32 v68, v68
	v_exp_f32_e32 v217, v84
	v_sub_f32_e32 v69, v69, v0
	v_sub_f32_e32 v84, v85, v0
	v_exp_f32_e32 v69, v69
	v_exp_f32_e32 v85, v84
	v_sub_f32_e32 v70, v70, v0
	v_sub_f32_e32 v86, v86, v0
	v_add_f32_e32 v83, v218, v66
	v_exp_f32_e32 v70, v70
	v_exp_f32_e32 v86, v86
	v_sub_f32_e32 v71, v71, v0
	v_sub_f32_e32 v87, v87, v0
	v_add_f32_e32 v83, 0, v83
	v_add_f32_e32 v199, v219, v67
	v_exp_f32_e32 v71, v71
	v_exp_f32_e32 v87, v87
	v_sub_f32_e32 v72, v72, v0
	v_sub_f32_e32 v88, v88, v0
	v_add_f32_e32 v83, v199, v83
	v_add_f32_e32 v84, v217, v68
	v_exp_f32_e32 v72, v72
	v_exp_f32_e32 v88, v88
	v_sub_f32_e32 v73, v73, v0
	v_sub_f32_e32 v89, v89, v0
	v_add_f32_e32 v83, v84, v83
	v_add_f32_e32 v84, v85, v69
	v_exp_f32_e32 v73, v73
	v_exp_f32_e32 v89, v89
	v_sub_f32_e32 v74, v74, v0
	v_sub_f32_e32 v90, v90, v0
	v_add_f32_e32 v83, v84, v83
	v_add_f32_e32 v84, v86, v70
	v_exp_f32_e32 v74, v74
	v_exp_f32_e32 v90, v90
	v_sub_f32_e32 v75, v75, v0
	v_sub_f32_e32 v91, v91, v0
	v_add_f32_e32 v83, v84, v83
	v_add_f32_e32 v84, v87, v71
	v_exp_f32_e32 v75, v75
	v_exp_f32_e32 v91, v91
	v_sub_f32_e32 v76, v76, v0
	v_sub_f32_e32 v92, v92, v0
	v_add_f32_e32 v83, v84, v83
	v_add_f32_e32 v84, v88, v72
	v_exp_f32_e32 v76, v76
	v_exp_f32_e32 v92, v92
	v_sub_f32_e32 v77, v77, v0
	v_sub_f32_e32 v93, v93, v0
	v_add_f32_e32 v83, v84, v83
	v_add_f32_e32 v84, v89, v73
	v_exp_f32_e32 v77, v77
	v_exp_f32_e32 v93, v93
	v_sub_f32_e32 v78, v78, v0
	v_sub_f32_e32 v94, v94, v0
	v_add_f32_e32 v83, v84, v83
	v_add_f32_e32 v84, v90, v74
	v_exp_f32_e32 v78, v78
	v_exp_f32_e32 v94, v94
	v_sub_f32_e32 v79, v79, v0
	v_sub_f32_e32 v95, v95, v0
	v_add_f32_e32 v83, v84, v83
	v_add_f32_e32 v84, v91, v75
	v_exp_f32_e32 v79, v79
	v_exp_f32_e32 v95, v95
	v_sub_f32_e32 v80, v80, v0
	v_sub_f32_e32 v96, v96, v0
	v_sub_f32_e32 v81, v81, v0
	v_add_f32_e32 v83, v84, v83
	v_add_f32_e32 v84, v92, v76
	v_exp_f32_e32 v80, v80
	v_exp_f32_e32 v96, v96
	v_exp_f32_e32 v239, v81
	v_sub_f32_e32 v81, v97, v0
	v_add_f32_e32 v83, v84, v83
	v_add_f32_e32 v84, v93, v77
	v_exp_f32_e32 v81, v81
	v_add_f32_e32 v83, v84, v83
	v_add_f32_e32 v84, v94, v78
	v_add_f32_e32 v83, v84, v83
	v_add_f32_e32 v84, v95, v79
	v_add_f32_e32 v83, v84, v83
	v_add_f32_e32 v84, v96, v80
	v_exp_f32_e32 v82, v82
	v_add_f32_e32 v83, v84, v83
	v_add_f32_e32 v84, v81, v239
	v_add_f32_e32 v83, v84, v83
	v_mov_b32_e32 v84, v83
	s_nop 1
	v_permlane32_swap_b32_e32 v83, v84
	v_cmp_gt_f32_e32 vcc, 1.0, v82
	s_cbranch_vccz .LBB0_802
	s_and_saveexec_b64 s[42:43], s[36:37]
	ds_write_b32 v190, v82
	s_or_b64 exec, exec, s[42:43]
	s_waitcnt lgkmcnt(0)
	ds_read_b128 v[240:243], v209 offset:96
	ds_read_b128 v[244:247], v209 offset:64
	ds_read_b128 v[248:251], v209 offset:32
	ds_read_b128 v[220:223], v209
	s_waitcnt lgkmcnt(3)
	v_pk_mul_f32 v[62:63], v[62:63], v[240:241]
	s_waitcnt lgkmcnt(2)
	v_pk_mul_f32 v[58:59], v[58:59], v[244:245]
	s_waitcnt lgkmcnt(1)
	v_pk_mul_f32 v[54:55], v[54:55], v[248:249]
	v_pk_mul_f32 v[64:65], v[64:65], v[242:243]
	v_pk_mul_f32 v[60:61], v[60:61], v[246:247]
	v_pk_mul_f32 v[56:57], v[56:57], v[250:251]
	s_waitcnt lgkmcnt(0)
	v_pk_mul_f32 v[52:53], v[52:53], v[222:223]
	v_pk_mul_f32 v[50:51], v[50:51], v[220:221]
	v_pk_mul_f32 v[46:47], v[46:47], v[240:241]
	v_pk_mul_f32 v[42:43], v[42:43], v[244:245]
	v_pk_mul_f32 v[38:39], v[38:39], v[248:249]
	v_pk_mul_f32 v[48:49], v[48:49], v[242:243]
	v_pk_mul_f32 v[44:45], v[44:45], v[246:247]
	v_pk_mul_f32 v[40:41], v[40:41], v[250:251]
	v_pk_mul_f32 v[36:37], v[36:37], v[222:223]
	v_pk_mul_f32 v[34:35], v[34:35], v[220:221]
	v_pk_mul_f32 v[30:31], v[30:31], v[240:241]
	v_pk_mul_f32 v[26:27], v[26:27], v[244:245]
	v_pk_mul_f32 v[22:23], v[22:23], v[248:249]
	v_pk_mul_f32 v[32:33], v[32:33], v[242:243]
	v_pk_mul_f32 v[28:29], v[28:29], v[246:247]
	v_pk_mul_f32 v[24:25], v[24:25], v[250:251]
	v_pk_mul_f32 v[20:21], v[20:21], v[222:223]
	v_pk_mul_f32 v[18:19], v[18:19], v[220:221]
	v_pk_mul_f32 v[14:15], v[14:15], v[240:241]
	v_pk_mul_f32 v[10:11], v[10:11], v[244:245]
	v_pk_mul_f32 v[6:7], v[6:7], v[248:249]
	v_pk_mul_f32 v[16:17], v[16:17], v[242:243]
	v_pk_mul_f32 v[12:13], v[12:13], v[246:247]
	v_pk_mul_f32 v[8:9], v[8:9], v[250:251]
	v_pk_mul_f32 v[4:5], v[4:5], v[222:223]
	v_pk_mul_f32 v[2:3], v[2:3], v[220:221]

; __device__ __forceinline__ int v_rd_base(int lane) { return ((lane & 3) << 3) | (((lane >> 2) & 3) << 6) | (((lane >> 4) & 1) << 5) | (((lane >> 5) & 1) << 8); }
; __device__ __forceinline__ void attn_mfma(LAS unsigned char* lds, int layer, int G, const int wave_s) {
;     ...
;             { const int vb = (int)(lbase + bf * AT_BUF + 32768 + kv * 16384) + v_rd_base(lane);
;               pv_one4<0>(o[0], vb, pa0, pa1, pa2, pa3); pv_one4<1>(o[1], vb, pa0, pa1, pa2, pa3); pv_one4<2>(o[2], vb, pa0, pa1, pa2, pa3); pv_one4<3>(o[3], vb, pa0, pa1, pa2, pa3); }
;             if (i + 1 < NT) AT_SWRITE(bf ^ 1);
.LBB0_808:
	v_add_u32_e32 v85, s71, v191
	ds_read_b64_tr_b16 v[86:87], v85 offset:0
	ds_read_b64_tr_b16 v[88:89], v85 offset:0x800
	ds_read_b64_tr_b16 v[90:91], v85 offset:0x1000
	ds_read_b64_tr_b16 v[92:93], v85 offset:0x1800
	ds_read_b64_tr_b16 v[94:95], v85 offset:0x2000
	ds_read_b64_tr_b16 v[96:97], v85 offset:0x2800
	ds_read_b64_tr_b16 v[218:219], v85 offset:0x3000
	ds_read_b64_tr_b16 v[220:221], v85 offset:0x3800
	s_waitcnt lgkmcnt(0)
	s_nop 0
	v_mfma_f32_32x32x16_bf16 v[50:65], v[66:69], v[86:89], v[50:65]
	ds_read_b64_tr_b16 v[86:87], v85 offset:0x200
	ds_read_b64_tr_b16 v[88:89], v85 offset:0xa00
	v_mfma_f32_32x32x16_bf16 v[50:65], v[70:73], v[90:93], v[50:65]
	ds_read_b64_tr_b16 v[90:91], v85 offset:0x1200
	ds_read_b64_tr_b16 v[92:93], v85 offset:0x1a00
	v_mfma_f32_32x32x16_bf16 v[50:65], v[74:77], v[94:97], v[50:65]
	ds_read_b64_tr_b16 v[94:95], v85 offset:0x2200
	ds_read_b64_tr_b16 v[96:97], v85 offset:0x2a00
	v_mfma_f32_32x32x16_bf16 v[50:65], v[78:81], v[218:221], v[50:65]
	ds_read_b64_tr_b16 v[218:219], v85 offset:0x3200
	ds_read_b64_tr_b16 v[220:221], v85 offset:0x3a00
	s_waitcnt lgkmcnt(0)
	v_mfma_f32_32x32x16_bf16 v[34:49], v[66:69], v[86:89], v[34:49]
	ds_read_b64_tr_b16 v[86:87], v85 offset:0x400
	ds_read_b64_tr_b16 v[88:89], v85 offset:0xc00
	v_mfma_f32_32x32x16_bf16 v[34:49], v[70:73], v[90:93], v[34:49]
	ds_read_b64_tr_b16 v[90:91], v85 offset:0x1400
	ds_read_b64_tr_b16 v[92:93], v85 offset:0x1c00
	v_mfma_f32_32x32x16_bf16 v[34:49], v[74:77], v[94:97], v[34:49]
	ds_read_b64_tr_b16 v[94:95], v85 offset:0x2400
	ds_read_b64_tr_b16 v[96:97], v85 offset:0x2c00
	v_mfma_f32_32x32x16_bf16 v[34:49], v[78:81], v[218:221], v[34:49]
	ds_read_b64_tr_b16 v[218:219], v85 offset:0x3400
	ds_read_b64_tr_b16 v[220:221], v85 offset:0x3c00
	s_waitcnt lgkmcnt(0)
	v_mfma_f32_32x32x16_bf16 v[18:33], v[66:69], v[86:89], v[18:33]
	ds_read_b64_tr_b16 v[86:87], v85 offset:0x600
	ds_read_b64_tr_b16 v[88:89], v85 offset:0xe00
	v_mfma_f32_32x32x16_bf16 v[18:33], v[70:73], v[90:93], v[18:33]
	ds_read_b64_tr_b16 v[90:91], v85 offset:0x1600
	ds_read_b64_tr_b16 v[92:93], v85 offset:0x1e00
	v_mfma_f32_32x32x16_bf16 v[18:33], v[74:77], v[94:97], v[18:33]
	ds_read_b64_tr_b16 v[94:95], v85 offset:0x2600
	ds_read_b64_tr_b16 v[96:97], v85 offset:0x2e00
	v_mfma_f32_32x32x16_bf16 v[18:33], v[78:81], v[218:221], v[18:33]
	ds_read_b64_tr_b16 v[218:219], v85 offset:0x3600
	ds_read_b64_tr_b16 v[220:221], v85 offset:0x3e00
	s_waitcnt lgkmcnt(0)
	v_mfma_f32_32x32x16_bf16 v[2:17], v[66:69], v[86:89], v[2:17]
	s_andn2_b64 vcc, exec, s[54:55]
	v_mfma_f32_32x32x16_bf16 v[2:17], v[70:73], v[90:93], v[2:17]
	v_mfma_f32_32x32x16_bf16 v[2:17], v[74:77], v[94:97], v[2:17]
	v_mfma_f32_32x32x16_bf16 v[2:17], v[78:81], v[218:221], v[2:17]
	s_cbranch_vccnz .LBB0_810
	s_xor_b32 s42, s71, 0x10000
	v_add_u32_e32 v67, s42, v233
	v_add_u32_e32 v66, s42, v234
	s_waitcnt vmcnt(7)
	ds_write_b128 v67, v[130:133]
	s_waitcnt vmcnt(6)
	ds_write_b128 v67, v[134:137] offset:16384
	s_waitcnt vmcnt(5)
	ds_write_b128 v66, v[138:141] offset:32768
	s_waitcnt vmcnt(4)
	ds_write_b128 v66, v[142:145] offset:49152
	s_waitcnt vmcnt(3)
	ds_write_b128 v67, v[146:149] offset:8192
	s_waitcnt vmcnt(2)
	ds_write_b128 v67, v[150:153] offset:24576
	s_waitcnt vmcnt(1)
	ds_write_b128 v66, v[154:157] offset:40960
	s_waitcnt vmcnt(0)
	ds_write_b128 v66, v[158:161] offset:57344
